# attention chunk loop: the two cross-lane row-max exchanges (lane^16, lane^32) use v_permlane16_swap / v_permlane32_swap instead of ds_bpermute round trips
# baseline (speedup 1.0000x reference)
; #define LAS __attribute__((address_space(3)))
; __device__ __forceinline__ f32x4 mfma16(bf16x8 a, bf16x8 b, f32x4 c) { return __builtin_amdgcn_mfma_f32_16x16x32_bf16(a, b, c, 0, 0, 0); }
; __device__ __forceinline__ void lds_barrier() { asm volatile("s_waitcnt lgkmcnt(0)" ::: "memory"); __builtin_amdgcn_s_barrier(); asm volatile("" ::: "memory"); }
; #define ATT_LOAD(jj_) do { const bf16_t* kb_ = zb + (size_t)((c - 8 + (jj_)) * 64 + skey) * ZLD + hp * 128 + spc * 8; \
;         kr[0] = *(const u32x4*)(kb_ + 256); vr[0] = *(const u32x4*)(kb_ + 512); kr[1] = *(const u32x4*)(kb_ + (size_t)32 * ZLD + 256); vr[1] = *(const u32x4*)(kb_ + (size_t)32 * ZLD + 512); } while (0)
; __device__ __forceinline__ void attn_item(const Params& p, int l, int item, LAS unsigned char* lds) {
;     ...
;     for (int jj = jj0; jj <= 8; ++jj) {
;         LAS unsigned char* Kb = lds + (jj & 1) * BUFB; LAS unsigned char* Vb = Kb + KBUF;
;         *(LAS u32x4*)(Kb + skey * KST + spc * 16) = kr[0]; *(LAS u32x4*)(Kb + (skey + 32) * KST + spc * 16) = kr[1];
;         *(LAS u32x4*)(Vb + skey * VST + spc * 16) = vr[0]; *(LAS u32x4*)(Vb + (skey + 32) * VST + spc * 16) = vr[1];
;         if (jj < 8) ATT_LOAD(jj + 1);
;         lds_barrier();
;         f32x4 s[4];
; #pragma unroll
;         for (int kt = 0; kt < 4; ++kt) { const LAS unsigned char* kp = Kb + (kt * 16 + fr) * KST + hh * 128 + fq * 16;
;             s[kt] = mfma16(*(const LAS bf16x8*)kp, qf0, ZERO4); s[kt] = mfma16(*(const LAS bf16x8*)(kp + 64), qf1, s[kt]); }
;         const int base = (8 - jj) * 64 + q0 + fr;
;         float cmax = -1e30f;
; #pragma unroll
;         for (int kt = 0; kt < 4; ++kt)
; #pragma unroll
;             for (int j = 0; j < 4; ++j) { const int dist = base - (kt * 16 + fq * 4 + j); const int idx = (dist < 256 ? dist : 256) + 63;
;                 const float sv = s[kt][j] * (0.125f * LOG2E) + bias_s[hh * 320 + idx]; s[kt][j] = sv; cmax = fmaxf(cmax, sv); }
.LBB0_412:
	v_add_u32_e32 v69, s15, v62
	v_add3_u32 v87, v69, v52, v65
	v_add3_u32 v69, v69, v64, v66
	v_add_u32_e32 v71, s14, v67
	s_sub_i32 s14, s14, 64
	v_add_u32_e32 v88, 0x200, v71
	v_min_i32_e32 v88, 0x100, v88
	v_lshl_add_u32 v88, v88, 2, v63
	v_add_u32_e32 v89, 0x1ff, v71
	v_min_i32_e32 v89, 0x100, v89
	v_lshl_add_u32 v89, v89, 2, v63
	v_add_u32_e32 v90, 0x1fe, v71
	v_min_i32_e32 v90, 0x100, v90
	v_lshl_add_u32 v90, v90, 2, v63
	v_add_u32_e32 v91, 0x1fd, v71
	v_min_i32_e32 v91, 0x100, v91
	v_lshl_add_u32 v91, v91, 2, v63
	v_add_u32_e32 v92, 0x1f0, v71
	v_min_i32_e32 v92, 0x100, v92
	v_lshl_add_u32 v92, v92, 2, v63
	v_add_u32_e32 v93, 0x1ef, v71
	v_min_i32_e32 v93, 0x100, v93
	v_lshl_add_u32 v93, v93, 2, v63
	v_add_u32_e32 v94, 0x1ee, v71
	v_min_i32_e32 v94, 0x100, v94
	v_lshl_add_u32 v94, v94, 2, v63
	v_add_u32_e32 v95, 0x1ed, v71
	v_min_i32_e32 v95, 0x100, v95
	v_lshl_add_u32 v95, v95, 2, v63
	v_add_u32_e32 v96, 0x1e0, v71
	v_min_i32_e32 v96, 0x100, v96
	v_lshl_add_u32 v96, v96, 2, v63
	v_add_u32_e32 v97, 0x1df, v71
	v_min_i32_e32 v97, 0x100, v97
	v_lshl_add_u32 v97, v97, 2, v63
	v_add_u32_e32 v98, 0x1de, v71
	v_min_i32_e32 v98, 0x100, v98
	v_lshl_add_u32 v98, v98, 2, v63
	v_add_u32_e32 v99, 0x1dd, v71
	v_min_i32_e32 v99, 0x100, v99
	v_lshl_add_u32 v99, v99, 2, v63
	v_add_u32_e32 v100, 0x1d0, v71
	v_min_i32_e32 v100, 0x100, v100
	v_lshl_add_u32 v100, v100, 2, v63
	v_add_u32_e32 v101, 0x1cf, v71
	v_min_i32_e32 v101, 0x100, v101
	v_lshl_add_u32 v101, v101, 2, v63
	v_add_u32_e32 v102, 0x1ce, v71
	v_min_i32_e32 v102, 0x100, v102
	v_lshl_add_u32 v102, v102, 2, v63
	v_add_u32_e32 v103, 0x1cd, v71
	v_min_i32_e32 v103, 0x100, v103
	v_lshl_add_u32 v103, v103, 2, v63
	s_mov_b64 s[16:17], 0x58000
	v_lshl_add_u64 v[56:57], v[56:57], 0, s[16:17]
	v_and_b32_e32 v47, 64, v207
	v_xor_b32_e32 v45, 16, v207
	v_add_u32_e32 v47, 64, v47
	v_cmp_lt_i32_e32 vcc, v45, v47
	v_xor_b32_e32 v46, 32, v207
	s_nop 1
	v_cndmask_b32_e32 v45, v207, v45, vcc
	v_cmp_lt_i32_e32 vcc, v46, v47
	v_lshlrev_b32_e32 v45, 2, v45
	s_nop 1
	v_cndmask_b32_e32 v46, v207, v46, vcc
	v_lshlrev_b32_e32 v46, 2, v46
	s_waitcnt lgkmcnt(0)
	s_barrier
; #define LAS __attribute__((address_space(3)))
; __device__ __forceinline__ unsigned pk2s(float lo, float hi) { unsigned r; asm("s_nop 0\n\tv_cvt_pk_bf16_f32 %0, %1, %2" : "=v"(r) : "v"(lo), "v"(hi)); return r; }
; __device__ __forceinline__ void attn_item(const Params& p, int l, int item, LAS unsigned char* lds) {
;     ...
;         f32x4 s[4];
; #pragma unroll
;         for (int kt = 0; kt < 4; ++kt) { const LAS unsigned char* kp = Kb + (kt * 16 + fr) * KST + hh * 128 + fq * 16;
;             s[kt] = mfma16(*(const LAS bf16x8*)kp, qf0, ZERO4); s[kt] = mfma16(*(const LAS bf16x8*)(kp + 64), qf1, s[kt]); }
;         const int base = (8 - jj) * 64 + q0 + fr;
;         float cmax = -1e30f;
; #pragma unroll
;         for (int kt = 0; kt < 4; ++kt)
; #pragma unroll
;             for (int j = 0; j < 4; ++j) { const int dist = base - (kt * 16 + fq * 4 + j); const int idx = (dist < 256 ? dist : 256) + 63;
;                 const float sv = s[kt][j] * (0.125f * LOG2E) + bias_s[hh * 320 + idx]; s[kt][j] = sv; cmax = fmaxf(cmax, sv); }
;         cmax = fmaxf(cmax, __shfl_xor(cmax, 16)); cmax = fmaxf(cmax, __shfl_xor(cmax, 32));
;         const float mnew = fmaxf(mrun, cmax), alpha = fexp2(mrun - mnew); mrun = mnew;
;         float ps = 0.f;
; #pragma unroll
;         for (int kt = 0; kt < 4; ++kt)
; #pragma unroll
;             for (int j = 0; j < 4; ++j) { const float e = fexp2(s[kt][j] - mnew); s[kt][j] = e; ps += e; }
;         lsum = lsum * alpha + ps;
; #pragma unroll
;         for (int dt = 0; dt < 4; ++dt) o[dt] *= alpha;
; #pragma unroll
;         for (int i = 0; i < 2; ++i) {
;             u32x4 pw; pw.x = pk2s(s[2 * i][0], s[2 * i][1]); pw.y = pk2s(s[2 * i][2], s[2 * i][3]); pw.z = pk2s(s[2 * i + 1][0], s[2 * i + 1][1]); pw.w = pk2s(s[2 * i + 1][2], s[2 * i + 1][3]);
;             const bf16x8 pb = as_bf8(pw);
;             const LAS unsigned char* vp = Vb + (32 * i + 4 * fq + (fr >> 2)) * VST + hh * 128 + (fr & 3) * 8;
; #pragma unroll
;             for (int dt = 0; dt < 4; ++dt) {
;                 const v4i16_t a0 = __builtin_amdgcn_ds_read_tr16_b64_v4i16((LAS v4i16_t*)(vp + dt * 32));
;                 const v4i16_t a1 = __builtin_amdgcn_ds_read_tr16_b64_v4i16((LAS v4i16_t*)(vp + 16 * VST + dt * 32));
;                 const bf16x8 av = __builtin_shufflevector(a0, a1, 0, 1, 2, 3, 4, 5, 6, 7);
;                 o[dt] = mfma16(av, pb, o[dt]); }
	ds_read_b32 v88, v88 offset:252
	ds_read_b32 v89, v89 offset:252
	ds_read_b32 v90, v90 offset:252
	ds_read_b32 v91, v91 offset:252
	ds_read_b32 v92, v92 offset:252
	ds_read_b32 v93, v93 offset:252
	ds_read_b32 v94, v94 offset:252
	ds_read_b32 v95, v95 offset:252
	ds_read_b32 v96, v96 offset:252
	ds_read_b32 v97, v97 offset:252
	ds_read_b32 v98, v98 offset:252
	ds_read_b32 v99, v99 offset:252
	ds_read_b32 v100, v100 offset:252
	ds_read_b32 v101, v101 offset:252
	ds_read_b32 v102, v102 offset:252
	ds_read_b32 v103, v103 offset:252
	ds_read_b128 v[104:107], v87 offset:0
	ds_read_b128 v[108:111], v87 offset:64
	ds_read_b128 v[112:115], v87 offset:4352
	ds_read_b128 v[116:119], v87 offset:4416
	ds_read_b128 v[120:123], v87 offset:8704
	ds_read_b128 v[124:127], v87 offset:8768
	ds_read_b128 v[128:131], v87 offset:13056
	ds_read_b128 v[132:135], v87 offset:13120
	s_mov_b32 s15, 0xf149f2ca
	s_waitcnt lgkmcnt(7)
	v_mfma_f32_16x16x32_bf16 v[180:183], v[104:107], v[4:7], 0
	s_waitcnt lgkmcnt(6)
	v_mfma_f32_16x16x32_bf16 v[72:75], v[108:111], v[8:11], v[180:183]
	ds_read_b64_tr_b16 v[148:149], v69 offset:17408
	ds_read_b64_tr_b16 v[150:151], v69 offset:22016
	ds_read_b64_tr_b16 v[152:153], v69 offset:17440
	ds_read_b64_tr_b16 v[154:155], v69 offset:22048
	ds_read_b64_tr_b16 v[156:157], v69 offset:17472
	ds_read_b64_tr_b16 v[158:159], v69 offset:22080
	ds_read_b64_tr_b16 v[160:161], v69 offset:17504
	ds_read_b64_tr_b16 v[162:163], v69 offset:22112
	s_waitcnt lgkmcnt(13)
	v_mfma_f32_16x16x32_bf16 v[184:187], v[112:115], v[4:7], 0
	s_waitcnt lgkmcnt(12)
	v_mfma_f32_16x16x32_bf16 v[76:79], v[116:119], v[8:11], v[184:187]
	s_waitcnt lgkmcnt(11)
	v_mfma_f32_16x16x32_bf16 v[188:191], v[120:123], v[4:7], 0
	s_waitcnt lgkmcnt(10)
	v_mfma_f32_16x16x32_bf16 v[48:51], v[124:127], v[8:11], v[188:191]
	s_waitcnt lgkmcnt(9)
	v_mfma_f32_16x16x32_bf16 v[192:195], v[128:131], v[4:7], 0
	s_waitcnt lgkmcnt(8)
	v_mfma_f32_16x16x32_bf16 v[80:83], v[132:135], v[8:11], v[192:195]
	v_fmac_f32_e32 v88, 0x3e38aa3b, v72
	v_fmac_f32_e32 v89, 0x3e38aa3b, v73
	v_fmac_f32_e32 v90, 0x3e38aa3b, v74
	v_fmac_f32_e32 v91, 0x3e38aa3b, v75
	v_fmac_f32_e32 v92, 0x3e38aa3b, v76
	v_fmac_f32_e32 v93, 0x3e38aa3b, v77
	v_fmac_f32_e32 v94, 0x3e38aa3b, v78
	v_fmac_f32_e32 v95, 0x3e38aa3b, v79
	v_fmac_f32_e32 v96, 0x3e38aa3b, v48
	v_fmac_f32_e32 v97, 0x3e38aa3b, v49
	v_fmac_f32_e32 v98, 0x3e38aa3b, v50
	v_fmac_f32_e32 v99, 0x3e38aa3b, v51
	s_nop 7
	v_fmac_f32_e32 v100, 0x3e38aa3b, v80
	v_fmac_f32_e32 v101, 0x3e38aa3b, v81
	v_fmac_f32_e32 v102, 0x3e38aa3b, v82
	v_fmac_f32_e32 v103, 0x3e38aa3b, v83
	v_max3_f32 v196, v88, s15, v89
	v_max3_f32 v196, v196, v90, v91
	v_max3_f32 v196, v196, v92, v93
	v_max3_f32 v196, v196, v94, v95
	v_max3_f32 v196, v196, v96, v97
	v_max3_f32 v196, v196, v98, v99
	v_max3_f32 v196, v196, v100, v101
	v_max3_f32 v196, v196, v102, v103
	v_mov_b32_e32 v197, v196
	s_nop 1
	v_permlane16_swap_b32_e32 v197, v196
	v_max_f32_e32 v197, v196, v197
	v_mov_b32_e32 v47, v197
	s_nop 1
	v_permlane32_swap_b32_e32 v47, v197
	v_max3_f32 v47, v70, v197, v47
	ds_read_b64_tr_b16 v[164:165], v69 offset:26624
	ds_read_b64_tr_b16 v[166:167], v69 offset:31232
	ds_read_b64_tr_b16 v[168:169], v69 offset:26656
	ds_read_b64_tr_b16 v[170:171], v69 offset:31264
	ds_read_b64_tr_b16 v[172:173], v69 offset:26688
	ds_read_b64_tr_b16 v[174:175], v69 offset:31296
	ds_read_b64_tr_b16 v[176:177], v69 offset:26720
	ds_read_b64_tr_b16 v[178:179], v69 offset:31328
	v_sub_f32_e32 v70, v70, v47
	v_sub_f32_e32 v88, v88, v47
	v_sub_f32_e32 v89, v89, v47
	v_sub_f32_e32 v90, v90, v47
	v_sub_f32_e32 v91, v91, v47
	v_sub_f32_e32 v92, v92, v47
	v_sub_f32_e32 v93, v93, v47
	v_sub_f32_e32 v94, v94, v47
	v_sub_f32_e32 v95, v95, v47
	v_sub_f32_e32 v96, v96, v47
	v_sub_f32_e32 v97, v97, v47
	v_sub_f32_e32 v98, v98, v47
	v_sub_f32_e32 v99, v99, v47
	v_sub_f32_e32 v100, v100, v47
	v_sub_f32_e32 v101, v101, v47
	v_sub_f32_e32 v102, v102, v47
	v_sub_f32_e32 v103, v103, v47
	v_exp_f32_e32 v44, v70
	v_exp_f32_e32 v88, v88
	v_exp_f32_e32 v89, v89
	v_exp_f32_e32 v90, v90
	v_exp_f32_e32 v91, v91
	v_exp_f32_e32 v92, v92
	v_exp_f32_e32 v93, v93
	v_exp_f32_e32 v94, v94
	v_exp_f32_e32 v95, v95
	v_exp_f32_e32 v96, v96
	v_exp_f32_e32 v97, v97
	v_exp_f32_e32 v98, v98
	v_exp_f32_e32 v99, v99
	v_exp_f32_e32 v100, v100
	v_exp_f32_e32 v101, v101
	v_exp_f32_e32 v102, v102
	v_exp_f32_e32 v103, v103
	v_pk_mul_f32 v[28:29], v[28:29], v[44:45] op_sel_hi:[1,0]
	v_pk_mul_f32 v[30:31], v[30:31], v[44:45] op_sel_hi:[1,0]
	v_pk_mul_f32 v[32:33], v[32:33], v[44:45] op_sel_hi:[1,0]
	v_pk_mul_f32 v[34:35], v[34:35], v[44:45] op_sel_hi:[1,0]
	v_pk_mul_f32 v[36:37], v[36:37], v[44:45] op_sel_hi:[1,0]
	v_pk_mul_f32 v[38:39], v[38:39], v[44:45] op_sel_hi:[1,0]
	v_pk_mul_f32 v[40:41], v[40:41], v[44:45] op_sel_hi:[1,0]
	v_pk_mul_f32 v[42:43], v[42:43], v[44:45] op_sel_hi:[1,0]
	v_add_f32_e32 v48, 0, v88
	v_add_f32_e32 v48, v89, v48
	v_add_f32_e32 v48, v90, v48
	v_add_f32_e32 v48, v91, v48
	v_add_f32_e32 v48, v92, v48
	v_add_f32_e32 v48, v93, v48
	v_add_f32_e32 v48, v94, v48
	v_add_f32_e32 v48, v95, v48
	v_add_f32_e32 v48, v96, v48
	v_add_f32_e32 v48, v97, v48
	v_add_f32_e32 v48, v98, v48
	v_add_f32_e32 v48, v99, v48
	v_add_f32_e32 v48, v100, v48
	v_add_f32_e32 v48, v101, v48
	v_add_f32_e32 v48, v102, v48
	v_add_f32_e32 v48, v103, v48
	v_fmac_f32_e32 v48, v68, v44
	v_cvt_pk_bf16_f32 v198, v88, v89
	v_cvt_pk_bf16_f32 v199, v90, v91
	v_cvt_pk_bf16_f32 v200, v92, v93
	v_cvt_pk_bf16_f32 v201, v94, v95
	v_cvt_pk_bf16_f32 v214, v96, v97
	v_cvt_pk_bf16_f32 v215, v98, v99
	v_cvt_pk_bf16_f32 v216, v100, v101
	v_cvt_pk_bf16_f32 v217, v102, v103
	s_add_i32 s15, s7, 1
	s_waitcnt lgkmcnt(8)
	v_mfma_f32_16x16x32_bf16 v[28:31], v[148:151], v[198:201], v[28:31]
	v_mfma_f32_16x16x32_bf16 v[32:35], v[152:155], v[198:201], v[32:35]
	v_mfma_f32_16x16x32_bf16 v[36:39], v[156:159], v[198:201], v[36:39]
	v_mfma_f32_16x16x32_bf16 v[40:43], v[160:163], v[198:201], v[40:43]
	s_waitcnt lgkmcnt(0)
	v_mfma_f32_16x16x32_bf16 v[28:31], v[164:167], v[214:217], v[28:31]
	v_mfma_f32_16x16x32_bf16 v[32:35], v[168:171], v[214:217], v[32:35]
	v_mfma_f32_16x16x32_bf16 v[36:39], v[172:175], v[214:217], v[36:39]
	v_mfma_f32_16x16x32_bf16 v[40:43], v[176:179], v[214:217], v[40:43]
	s_cmp_lt_u32 s7, 8
	s_cbranch_scc0 .LBB0_425
	v_mov_b32_e32 v70, v47
	v_mov_b32_e32 v68, v48
	s_mov_b32 s7, s15
	s_branch .LBB0_410
